# context tiles of the N=1024 GEMMs cut into 8 split-K parts instead of 4 (256 parts: every CU busy in the second round); the norm phase sums 8 parts
# baseline (speedup 1.0000x reference)
;     __device__ void init(int M, int N, int G_, int c_, int K_, bool bd_) { base.init(M, N, G_, c_, K_); bd = bd_; }
;     __device__ void init(int M, int G_, int c_, int K_, int S_) {
;         lat.init(MLAT, DM, G_, c_, K_); all.init(M, DM, G_, c_, K_); G = G_; c = c_; S = S_; npairs = K_ / (2 * BK);
;         plain = (lat.nwg % G_) != 0 || M <= MLAT; nlr = lat.nwg / G_; nseg = ((M - MLAT) / BM) * 4 * S_;
;     }
;     __device__ bool next(int i, Unit& u) const {
;         if (plain) return all.next(i, u);
;         if (i < nlr) return lat.next(i, u);
;         const int sidx = (i - nlr) * G + c; if (sidx >= nseg) return false;
;         const int tile = sidx / S, part = sidx % S, p0 = part * npairs / S, p1 = (part + 1) * npairs / S;
;         u.pm = MLAT / BM + (tile >> 2); u.pn = tile & 3; u.kt0 = 2 * p0; u.ntk = 2 * (p1 - p0); u.part = part; return true;
.LBB0_395:
	s_and_b64 s[4:5], s[40:41], exec
	s_cselect_b32 s8, 5, 8
	s_cmp_lg_u32 s84, 2
	s_cselect_b64 s[4:5], -1, 0
	s_and_b64 s[6:7], s[4:5], exec
	s_cselect_b32 s7, s8, 2
	v_readlane_b32 s8, v255, 32
	v_readlane_b32 s9, v255, 33
	s_and_b64 s[4:5], s[8:9], s[4:5]
	s_xor_b64 s[42:43], s[4:5], -1
	s_and_b64 s[4:5], s[4:5], exec
	s_movk_i32 s4, 0x4800
	s_cselect_b32 s4, 0x4000, s4
	s_ashr_i32 s23, s22, 31
	s_lshr_b32 s5, s23, 26
	s_add_i32 s5, s22, s5
	s_ashr_i32 s87, s5, 6
	s_lshr_b32 s5, s23, 25
	s_add_i32 s5, s22, s5
	s_ashr_i32 s5, s5, 7
	v_writelane_b32 v255, s5, 36
	s_abs_i32 s5, s82
	v_cvt_f32_u32_e32 v0, s5
	s_sub_i32 s6, 0, s5
	s_ashr_i32 s88, s82, 31
	v_mov_b32_e32 v14, v196
	v_rcp_iflag_f32_e32 v0, v0
	s_mov_b64 s[52:53], -1
	s_waitcnt vmcnt(0) lgkmcnt(0)
	v_readfirstlane_b32 s47, v3
	v_readfirstlane_b32 s46, v2
	v_mul_f32_e32 v0, 0x4f7ffffe, v0
	v_cvt_u32_f32_e32 v0, v0
	s_nop 0
	v_readfirstlane_b32 s8, v0
	s_mul_i32 s6, s6, s8
	s_mul_hi_u32 s6, s8, s6
	s_add_i32 s8, s8, s6
	s_lshr_b32 s6, s8, 24
	s_mul_i32 s8, s6, s5
	s_sub_i32 s8, 0x100, s8
	s_add_i32 s9, s6, 1
	s_sub_i32 s10, s8, s5
	s_cmp_ge_u32 s8, s5
	s_cselect_b32 s6, s9, s6
	s_cselect_b32 s8, s10, s8
	s_add_i32 s9, s6, 1
	s_cmp_ge_u32 s8, s5
	s_cselect_b32 s5, s9, s6
	s_xor_b32 s5, s5, s88
	s_sub_i32 s89, s5, s88
	s_mul_i32 s6, s89, s82
	s_cmpk_eq_i32 s6, 0x100
	s_cselect_b64 s[8:9], -1, 0
	s_lshr_b32 s5, s4, 3
	s_and_b64 s[44:45], s[42:43], s[8:9]
	s_and_b32 s5, s5, 0x100
	s_and_b64 s[8:9], s[40:41], exec
	v_writelane_b32 v255, s5, 37
	s_cselect_b32 s48, 1.0, 0.5
	v_readfirstlane_b32 s5, v14
	s_and_b64 vcc, exec, s[44:45]
	s_cbranch_vccz .LBB0_408
	s_cmp_lt_i32 s89, 1
	s_cbranch_scc0 .LBB0_399
	s_sub_i32 s6, s83, s6
	v_readlane_b32 s8, v255, 37
	s_mov_b64 s[40:41], 0
	s_mov_b64 s[52:53], 0
	s_cmp_ge_i32 s6, s8
	s_mov_b64 s[50:51], 0
	s_cbranch_scc1 .LBB0_399
	s_ashr_i32 s8, s6, 31
	s_lshr_b32 s8, s8, 29
	s_add_i32 s8, s6, s8
	s_and_b32 s9, s8, -8
	s_sub_i32 s42, s6, s9
	v_readlane_b32 s10, v255, 36
	s_mul_i32 s6, s42, s10
	s_ashr_i32 s9, s6, 31
	s_lshr_b32 s9, s9, 29
	s_add_i32 s9, s6, s9
	s_add_i32 s6, s6, s10
	s_ashr_i32 s10, s6, 31
	s_lshr_b32 s10, s10, 29
	s_ashr_i32 s9, s9, 3
	s_add_i32 s6, s6, s10
	s_ashr_i32 s6, s6, 3
	s_ashr_i32 s10, s8, 5
	s_bfe_u32 s43, s8, 0x20003
	s_lshl_b32 s8, s9, 1
	s_sub_i32 s6, s6, s9
	s_ashr_i32 s9, s8, 31
	s_add_i32 s15, s10, 64
	s_lshl_b32 s86, s6, 1
	s_lshl_b64 s[40:41], s[8:9], 7
	s_mov_b64 s[50:51], -1

;     __device__ bool next(int i, Unit& u) const {
;         if (plain) return all.next(i, u);
;         if (i < nlr) return lat.next(i, u);
;         const int sidx = (i - nlr) * G + c; if (sidx >= nseg) return false;
;         const int tile = sidx / S, part = sidx % S, p0 = part * npairs / S, p1 = (part + 1) * npairs / S;
;         u.pm = MLAT / BM + (tile >> 2); u.pn = tile & 3; u.kt0 = 2 * p0; u.ntk = 2 * (p1 - p0); u.part = part; return true;
.LBB0_418:
	s_add_i32 s10, s10, 1
	s_mov_b64 s[40:41], -1
	s_and_b64 vcc, exec, s[44:45]
	s_cbranch_vccz .LBB0_430
	s_cmp_ge_i32 s10, s89
	s_cbranch_scc0 .LBB0_422
	s_sub_i32 s11, s10, s89
	s_mul_i32 s60, s11, s82
	s_add_i32 s60, s60, s83
	v_readlane_b32 s11, v255, 37
	s_mov_b64 s[40:41], 0
	s_cmp_ge_i32 s60, s11
	s_mov_b64 s[22:23], 0
	s_mov_b32 s11, s81
	s_mov_b32 s12, s80
	s_mov_b32 s72, s73
	s_mov_b32 s78, s14
	s_mov_b32 s21, s13
	s_cbranch_scc1 .LBB0_422
	s_ashr_i32 s11, s60, 31
	s_lshr_b32 s11, s11, 29
	s_add_i32 s12, s60, s11
	s_and_b32 s11, s12, -8
	s_sub_i32 s21, s60, s11
	v_readlane_b32 s23, v255, 36
	s_mul_i32 s11, s21, s23
	s_ashr_i32 s22, s11, 31
	s_lshr_b32 s22, s22, 29
	s_add_i32 s22, s11, s22
	s_add_i32 s11, s11, s23
	s_ashr_i32 s23, s11, 31
	s_lshr_b32 s23, s23, 29
	s_add_i32 s11, s11, s23
	s_ashr_i32 s22, s22, 3
	s_ashr_i32 s23, s11, 3
	s_ashr_i32 s11, s12, 5
	s_lshl_b32 s72, s22, 1
	s_sub_i32 s22, s23, s22
	s_add_i32 s11, s11, 64
	s_bfe_u32 s12, s12, 0x20003
	s_lshl_b32 s78, s22, 1
	s_mov_b64 s[22:23], -1

; #define GAS __attribute__((address_space(1)))
; __global__ void __launch_bounds__(512, 2) fwd_mega(Args args) {
;     ...
;                 const int r_first = ROWOF(0); const bool pf = haspart && nk > 0 && r_first >= MLAT;
; #pragma unroll
;                 for (int sq = 0; sq < SPLITS; ++sq) { pq[sq][0] = (u32x4){0u, 0u, 0u, 0u}; pq[sq][1] = pq[sq][0]; }
;                 if (pf) {
; #pragma unroll
;                     for (int sq = 0; sq < SPLITS; ++sq) { const GAS bf16* pr = (const GAS bf16*)(ws + WS_PART) + ((size_t)sq * MCTX + (r_first - MLAT)) * DM + 8 * lane;
;                         pq[sq][0] = *(const GAS u32x4*)pr; pq[sq][1] = *(const GAS u32x4*)(pr + 512); } }
.LBB0_822:
	s_cmpk_lt_i32 s8, 0x4000
	s_cselect_b64 s[10:11], -1, 0
	s_and_b64 s[12:13], s[40:41], s[14:15]
	s_xor_b64 s[12:13], s[12:13], -1
	s_or_b64 s[26:27], s[12:13], s[10:11]
	s_and_b64 vcc, exec, s[26:27]
	s_cbranch_vccnz .LBB0_826
	s_add_i32 s24, s8, 0xffffc000
	s_lshl_b64 s[8:9], s[24:25], 11
	s_add_u32 s8, s34, s8
	s_addc_u32 s9, s35, s9
	v_lshl_add_u64 v[2:3], v[108:109], 1, s[8:9]
	s_mov_b64 s[8:9], 0x17b00000
	v_add_co_u32_e32 v22, vcc, 0x17b00000, v2
	v_lshl_add_u64 v[20:21], v[2:3], 0, s[8:9]
	s_nop 0
	v_addc_co_u32_e32 v23, vcc, 0, v3, vcc
	global_load_dwordx4 v[96:99], v[22:23], off
	global_load_dwordx4 v[80:83], v[20:21], off offset:1024
	v_add_co_u32_e32 v20, vcc, 0x17f00000, v2
	s_nop 1
	v_addc_co_u32_e32 v21, vcc, 0, v3, vcc
	global_load_dwordx4 v[92:95], v[20:21], off
	global_load_dwordx4 v[76:79], v[20:21], off offset:1024
	v_add_co_u32_e32 v20, vcc, 0x18300000, v2
	s_nop 1
	v_addc_co_u32_e32 v21, vcc, 0, v3, vcc
	v_add_co_u32_e32 v2, vcc, 0x18700000, v2
	global_load_dwordx4 v[88:91], v[20:21], off
	global_load_dwordx4 v[72:75], v[20:21], off offset:1024
	v_addc_co_u32_e32 v3, vcc, 0, v3, vcc
	global_load_dwordx4 v[84:87], v[2:3], off
	global_load_dwordx4 v[68:71], v[2:3], off offset:1024
	v_add_co_u32_e32 v134, vcc, 0x400000, v2
	s_nop 1
	v_addc_co_u32_e32 v135, vcc, 0, v3, vcc
	global_load_dwordx4 v[140:143], v[134:135], off
	global_load_dwordx4 v[144:147], v[134:135], off offset:1024
	v_add_co_u32_e32 v134, vcc, 0x800000, v2
	s_nop 1
	v_addc_co_u32_e32 v135, vcc, 0, v3, vcc
	global_load_dwordx4 v[148:151], v[134:135], off
	global_load_dwordx4 v[152:155], v[134:135], off offset:1024
	v_add_co_u32_e32 v134, vcc, 0xc00000, v2
	s_nop 1
	v_addc_co_u32_e32 v135, vcc, 0, v3, vcc
	global_load_dwordx4 v[156:159], v[134:135], off
	global_load_dwordx4 v[160:163], v[134:135], off offset:1024
	v_add_co_u32_e32 v134, vcc, 0x1000000, v2
	s_nop 1
	v_addc_co_u32_e32 v135, vcc, 0, v3, vcc
	global_load_dwordx4 v[164:167], v[134:135], off
	global_load_dwordx4 v[168:171], v[134:135], off offset:1024
	s_andn2_b64 vcc, exec, s[40:41]
	s_cbranch_vccz .LBB0_827
	s_branch .LBB0_877

; #define GAS __attribute__((address_space(1)))
; __global__ void __launch_bounds__(512, 2) fwd_mega(Args args) {
;     ...
;                 u32x4 pq[SPLITS][2];
;                 const int r_first = ROWOF(0); const bool pf = haspart && nk > 0 && r_first >= MLAT;
; #pragma unroll
;                 for (int sq = 0; sq < SPLITS; ++sq) { pq[sq][0] = (u32x4){0u, 0u, 0u, 0u}; pq[sq][1] = pq[sq][0]; }
;                 if (pf) {
; #pragma unroll
;                     for (int sq = 0; sq < SPLITS; ++sq) { const GAS bf16* pr = (const GAS bf16*)(ws + WS_PART) + ((size_t)sq * MCTX + (r_first - MLAT)) * DM + 8 * lane;
;                         pq[sq][0] = *(const GAS u32x4*)pr; pq[sq][1] = *(const GAS u32x4*)(pr + 512); } }
.LBB0_826:
	v_mov_b32_e32 v2, v1
	v_mov_b32_e32 v3, v1
	v_mov_b32_e32 v0, v1
	v_mov_b64_e32 v[98:99], v[2:3]
	v_mov_b64_e32 v[82:83], v[2:3]
	v_mov_b64_e32 v[94:95], v[2:3]
	v_mov_b64_e32 v[78:79], v[2:3]
	v_mov_b64_e32 v[90:91], v[2:3]
	v_mov_b64_e32 v[74:75], v[2:3]
	v_mov_b64_e32 v[86:87], v[2:3]
	v_mov_b64_e32 v[70:71], v[2:3]
	v_mov_b64_e32 v[96:97], v[0:1]
	v_mov_b64_e32 v[80:81], v[0:1]
	v_mov_b64_e32 v[92:93], v[0:1]
	v_mov_b64_e32 v[76:77], v[0:1]
	v_mov_b64_e32 v[88:89], v[0:1]
	v_mov_b64_e32 v[72:73], v[0:1]
	v_mov_b64_e32 v[84:85], v[0:1]
	v_mov_b64_e32 v[68:69], v[0:1]
	v_mov_b64_e32 v[140:141], v[2:3]
	v_mov_b64_e32 v[142:143], v[2:3]
	v_mov_b64_e32 v[144:145], v[2:3]
	v_mov_b64_e32 v[146:147], v[2:3]
	v_mov_b64_e32 v[148:149], v[2:3]
	v_mov_b64_e32 v[150:151], v[2:3]
	v_mov_b64_e32 v[152:153], v[2:3]
	v_mov_b64_e32 v[154:155], v[2:3]
	v_mov_b64_e32 v[156:157], v[2:3]
	v_mov_b64_e32 v[158:159], v[2:3]
	v_mov_b64_e32 v[160:161], v[2:3]
	v_mov_b64_e32 v[162:163], v[2:3]
	v_mov_b64_e32 v[164:165], v[2:3]
	v_mov_b64_e32 v[166:167], v[2:3]
	v_mov_b64_e32 v[168:169], v[2:3]
	v_mov_b64_e32 v[170:171], v[2:3]
	s_andn2_b64 vcc, exec, s[40:41]
	s_cbranch_vccnz .LBB0_877

; #define GAS __attribute__((address_space(1)))
; __device__ __forceinline__ unsigned cvtpk(float lo, float hi) { f32x2_t v = {lo, hi}; bf16x2_t b = __builtin_convertvector(v, bf16x2_t); return __builtin_bit_cast(unsigned, b); }
; __global__ void __launch_bounds__(512, 2) fwd_mega(Args args) {
;     ...
;                     if (haspart && r >= MLAT) {
; #pragma unroll
;                         for (int sq = 0; sq < SPLITS; ++sq) { const GAS bf16* pr = (const GAS bf16*)(ws + WS_PART) + ((size_t)sq * MCTX + (r - MLAT)) * DM + 8 * lane;
; #pragma unroll
;                             for (int j = 0; j < 2; ++j) { const u32x4 a = (pf && k == 0) ? pq[sq][j] : *(const GAS u32x4*)(pr + 512 * j);
;                                 v[8 * j + 0] += __builtin_bit_cast(float, a.x << 16); v[8 * j + 1] += __builtin_bit_cast(float, a.x & 0xffff0000u); v[8 * j + 2] += __builtin_bit_cast(float, a.y << 16); v[8 * j + 3] += __builtin_bit_cast(float, a.y & 0xffff0000u);
;                                 v[8 * j + 4] += __builtin_bit_cast(float, a.z << 16); v[8 * j + 5] += __builtin_bit_cast(float, a.z & 0xffff0000u); v[8 * j + 6] += __builtin_bit_cast(float, a.w << 16); v[8 * j + 7] += __builtin_bit_cast(float, a.w & 0xffff0000u); } }
;                         GAS u32x4* xw = (GAS u32x4*)(X + (size_t)r * DM) + lane;
; #pragma unroll
;                         for (int j = 0; j < 2; ++j) { const u32x4 o = (u32x4){cvtpk(v[8 * j], v[8 * j + 1]), cvtpk(v[8 * j + 2], v[8 * j + 3]), cvtpk(v[8 * j + 4], v[8 * j + 5]), cvtpk(v[8 * j + 6], v[8 * j + 7])}; xw[64 * j] = o;
;                             v[8 * j + 0] = __builtin_bit_cast(float, o.x << 16); v[8 * j + 1] = __builtin_bit_cast(float, o.x & 0xffff0000u); v[8 * j + 2] = __builtin_bit_cast(float, o.y << 16); v[8 * j + 3] = __builtin_bit_cast(float, o.y & 0xffff0000u);
;                             v[8 * j + 4] = __builtin_bit_cast(float, o.z << 16); v[8 * j + 5] = __builtin_bit_cast(float, o.z & 0xffff0000u); v[8 * j + 6] = __builtin_bit_cast(float, o.w << 16); v[8 * j + 7] = __builtin_bit_cast(float, o.w & 0xffff0000u); }
.LBB0_855:
	s_waitcnt vmcnt(0)
	v_lshlrev_b32_e32 v102, 16, v96
	v_and_b32_e32 v103, 0xffff0000, v96
	v_lshlrev_b32_e32 v96, 16, v97
	v_and_b32_e32 v97, 0xffff0000, v97
	v_pk_add_f32 v[96:97], v[120:121], v[96:97]
	v_lshlrev_b32_e32 v120, 16, v98
	v_and_b32_e32 v121, 0xffff0000, v98
	v_lshlrev_b32_e32 v98, 16, v99
	v_and_b32_e32 v99, 0xffff0000, v99
	v_pk_add_f32 v[98:99], v[116:117], v[98:99]
	v_lshlrev_b32_e32 v116, 16, v92
	v_and_b32_e32 v117, 0xffff0000, v92
	v_lshlrev_b32_e32 v92, 16, v93
	v_and_b32_e32 v93, 0xffff0000, v93
	v_pk_add_f32 v[92:93], v[96:97], v[92:93]
	v_lshlrev_b32_e32 v96, 16, v94
	v_and_b32_e32 v97, 0xffff0000, v94
	v_lshlrev_b32_e32 v94, 16, v95
	v_and_b32_e32 v95, 0xffff0000, v95
	v_pk_add_f32 v[94:95], v[98:99], v[94:95]
	v_lshlrev_b32_e32 v98, 16, v88
	v_and_b32_e32 v99, 0xffff0000, v88
	v_lshlrev_b32_e32 v88, 16, v89
	v_and_b32_e32 v89, 0xffff0000, v89
	v_pk_add_f32 v[88:89], v[92:93], v[88:89]
	v_lshlrev_b32_e32 v92, 16, v90
	v_and_b32_e32 v93, 0xffff0000, v90
	v_lshlrev_b32_e32 v90, 16, v91
	v_and_b32_e32 v91, 0xffff0000, v91
	v_pk_add_f32 v[118:119], v[118:119], v[120:121]
	v_pk_add_f32 v[90:91], v[94:95], v[90:91]
	v_lshlrev_b32_e32 v94, 16, v84
	v_and_b32_e32 v95, 0xffff0000, v84
	v_lshlrev_b32_e32 v84, 16, v85
	v_and_b32_e32 v85, 0xffff0000, v85
	v_pk_add_f32 v[96:97], v[118:119], v[96:97]
	v_pk_add_f32 v[84:85], v[88:89], v[84:85]
	v_lshlrev_b32_e32 v88, 16, v86
	v_and_b32_e32 v89, 0xffff0000, v86
	v_lshlrev_b32_e32 v86, 16, v87
	v_and_b32_e32 v87, 0xffff0000, v87
	v_pk_add_f32 v[92:93], v[96:97], v[92:93]
	v_pk_add_f32 v[86:87], v[90:91], v[86:87]
	v_lshlrev_b32_e32 v90, 16, v80
	v_and_b32_e32 v91, 0xffff0000, v80
	v_lshlrev_b32_e32 v80, 16, v81
	v_and_b32_e32 v81, 0xffff0000, v81
	v_pk_add_f32 v[88:89], v[92:93], v[88:89]
	v_pk_add_f32 v[80:81], v[106:107], v[80:81]
	v_lshlrev_b32_e32 v92, 16, v82
	v_and_b32_e32 v93, 0xffff0000, v82
	v_lshlrev_b32_e32 v82, 16, v83
	v_and_b32_e32 v83, 0xffff0000, v83
	v_lshlrev_b32_e32 v96, 16, v76
	v_and_b32_e32 v97, 0xffff0000, v76
	v_lshlrev_b32_e32 v76, 16, v77
	v_and_b32_e32 v77, 0xffff0000, v77
	v_pk_add_f32 v[82:83], v[100:101], v[82:83]
	v_pk_add_f32 v[76:77], v[80:81], v[76:77]
	v_lshlrev_b32_e32 v80, 16, v78
	v_and_b32_e32 v81, 0xffff0000, v78
	v_lshlrev_b32_e32 v78, 16, v79
	v_and_b32_e32 v79, 0xffff0000, v79
	v_pk_add_f32 v[78:79], v[82:83], v[78:79]
	v_lshlrev_b32_e32 v82, 16, v72
	v_and_b32_e32 v83, 0xffff0000, v72
	v_lshlrev_b32_e32 v72, 16, v73
	v_and_b32_e32 v73, 0xffff0000, v73
	v_pk_add_f32 v[102:103], v[122:123], v[102:103]
	v_pk_add_f32 v[92:93], v[104:105], v[92:93]
	v_pk_add_f32 v[72:73], v[76:77], v[72:73]
	v_lshlrev_b32_e32 v76, 16, v74
	v_and_b32_e32 v77, 0xffff0000, v74
	v_lshlrev_b32_e32 v74, 16, v75
	v_and_b32_e32 v75, 0xffff0000, v75
	v_pk_add_f32 v[102:103], v[102:103], v[116:117]
	v_pk_add_f32 v[90:91], v[114:115], v[90:91]
	v_pk_add_f32 v[80:81], v[92:93], v[80:81]
	v_pk_add_f32 v[74:75], v[78:79], v[74:75]
	v_lshlrev_b32_e32 v78, 16, v68
	v_and_b32_e32 v79, 0xffff0000, v68
	v_lshlrev_b32_e32 v68, 16, v69
	v_and_b32_e32 v69, 0xffff0000, v69
	v_pk_add_f32 v[98:99], v[102:103], v[98:99]
	v_pk_add_f32 v[90:91], v[90:91], v[96:97]
	v_pk_add_f32 v[76:77], v[80:81], v[76:77]
	v_pk_add_f32 v[72:73], v[72:73], v[68:69]
	v_lshlrev_b32_e32 v68, 16, v70
	v_and_b32_e32 v69, 0xffff0000, v70
	s_mov_b32 s23, s25
	v_pk_add_f32 v[94:95], v[98:99], v[94:95]
	v_pk_add_f32 v[82:83], v[90:91], v[82:83]
	v_pk_add_f32 v[76:77], v[76:77], v[68:69]
	v_lshlrev_b32_e32 v68, 16, v71
	v_and_b32_e32 v69, 0xffff0000, v71
	s_lshl_b64 s[38:39], s[22:23], 11
	v_pk_add_f32 v[78:79], v[82:83], v[78:79]
	v_pk_add_f32 v[74:75], v[74:75], v[68:69]
	v_lshl_add_u64 v[80:81], v[110:111], 0, s[38:39]
	v_lshlrev_b32_e32 v136, 16, v140
	v_and_b32_e32 v137, 0xffff0000, v140
	v_pk_add_f32 v[94:95], v[94:95], v[136:137]
	v_lshlrev_b32_e32 v138, 16, v144
	v_and_b32_e32 v139, 0xffff0000, v144
	v_pk_add_f32 v[78:79], v[78:79], v[138:139]
	v_lshlrev_b32_e32 v136, 16, v141
	v_and_b32_e32 v137, 0xffff0000, v141
	v_pk_add_f32 v[84:85], v[84:85], v[136:137]
	v_lshlrev_b32_e32 v138, 16, v145
	v_and_b32_e32 v139, 0xffff0000, v145
	v_pk_add_f32 v[72:73], v[72:73], v[138:139]
; #define GAS __attribute__((address_space(1)))
; __device__ __forceinline__ unsigned cvtpk(float lo, float hi) { f32x2_t v = {lo, hi}; bf16x2_t b = __builtin_convertvector(v, bf16x2_t); return __builtin_bit_cast(unsigned, b); }
; __global__ void __launch_bounds__(512, 2) fwd_mega(Args args) {
;     ...
;                     if (haspart && r >= MLAT) {
; #pragma unroll
;                         for (int sq = 0; sq < SPLITS; ++sq) { const GAS bf16* pr = (const GAS bf16*)(ws + WS_PART) + ((size_t)sq * MCTX + (r - MLAT)) * DM + 8 * lane;
; #pragma unroll
;                             for (int j = 0; j < 2; ++j) { const u32x4 a = (pf && k == 0) ? pq[sq][j] : *(const GAS u32x4*)(pr + 512 * j);
;                                 v[8 * j + 0] += __builtin_bit_cast(float, a.x << 16); v[8 * j + 1] += __builtin_bit_cast(float, a.x & 0xffff0000u); v[8 * j + 2] += __builtin_bit_cast(float, a.y << 16); v[8 * j + 3] += __builtin_bit_cast(float, a.y & 0xffff0000u);
;                                 v[8 * j + 4] += __builtin_bit_cast(float, a.z << 16); v[8 * j + 5] += __builtin_bit_cast(float, a.z & 0xffff0000u); v[8 * j + 6] += __builtin_bit_cast(float, a.w << 16); v[8 * j + 7] += __builtin_bit_cast(float, a.w & 0xffff0000u); } }
;                         GAS u32x4* xw = (GAS u32x4*)(X + (size_t)r * DM) + lane;
; #pragma unroll
;                         for (int j = 0; j < 2; ++j) { const u32x4 o = (u32x4){cvtpk(v[8 * j], v[8 * j + 1]), cvtpk(v[8 * j + 2], v[8 * j + 3]), cvtpk(v[8 * j + 4], v[8 * j + 5]), cvtpk(v[8 * j + 6], v[8 * j + 7])}; xw[64 * j] = o;
;                             v[8 * j + 0] = __builtin_bit_cast(float, o.x << 16); v[8 * j + 1] = __builtin_bit_cast(float, o.x & 0xffff0000u); v[8 * j + 2] = __builtin_bit_cast(float, o.y << 16); v[8 * j + 3] = __builtin_bit_cast(float, o.y & 0xffff0000u);
;                             v[8 * j + 4] = __builtin_bit_cast(float, o.z << 16); v[8 * j + 5] = __builtin_bit_cast(float, o.z & 0xffff0000u); v[8 * j + 6] = __builtin_bit_cast(float, o.w << 16); v[8 * j + 7] = __builtin_bit_cast(float, o.w & 0xffff0000u); }
	v_lshlrev_b32_e32 v136, 16, v142
	v_and_b32_e32 v137, 0xffff0000, v142
	v_pk_add_f32 v[88:89], v[88:89], v[136:137]
	v_lshlrev_b32_e32 v138, 16, v146
	v_and_b32_e32 v139, 0xffff0000, v146
	v_pk_add_f32 v[76:77], v[76:77], v[138:139]
	v_lshlrev_b32_e32 v136, 16, v143
	v_and_b32_e32 v137, 0xffff0000, v143
	v_pk_add_f32 v[86:87], v[86:87], v[136:137]
	v_lshlrev_b32_e32 v138, 16, v147
	v_and_b32_e32 v139, 0xffff0000, v147
	v_pk_add_f32 v[74:75], v[74:75], v[138:139]
	v_lshlrev_b32_e32 v136, 16, v148
	v_and_b32_e32 v137, 0xffff0000, v148
	v_pk_add_f32 v[94:95], v[94:95], v[136:137]
	v_lshlrev_b32_e32 v138, 16, v152
	v_and_b32_e32 v139, 0xffff0000, v152
	v_pk_add_f32 v[78:79], v[78:79], v[138:139]
	v_lshlrev_b32_e32 v136, 16, v149
	v_and_b32_e32 v137, 0xffff0000, v149
	v_pk_add_f32 v[84:85], v[84:85], v[136:137]
	v_lshlrev_b32_e32 v138, 16, v153
	v_and_b32_e32 v139, 0xffff0000, v153
	v_pk_add_f32 v[72:73], v[72:73], v[138:139]
	v_lshlrev_b32_e32 v136, 16, v150
	v_and_b32_e32 v137, 0xffff0000, v150
	v_pk_add_f32 v[88:89], v[88:89], v[136:137]
	v_lshlrev_b32_e32 v138, 16, v154
	v_and_b32_e32 v139, 0xffff0000, v154
	v_pk_add_f32 v[76:77], v[76:77], v[138:139]
	v_lshlrev_b32_e32 v136, 16, v151
	v_and_b32_e32 v137, 0xffff0000, v151
	v_pk_add_f32 v[86:87], v[86:87], v[136:137]
	v_lshlrev_b32_e32 v138, 16, v155
	v_and_b32_e32 v139, 0xffff0000, v155
	v_pk_add_f32 v[74:75], v[74:75], v[138:139]
	v_lshlrev_b32_e32 v136, 16, v156
	v_and_b32_e32 v137, 0xffff0000, v156
	v_pk_add_f32 v[94:95], v[94:95], v[136:137]
	v_lshlrev_b32_e32 v138, 16, v160
	v_and_b32_e32 v139, 0xffff0000, v160
	v_pk_add_f32 v[78:79], v[78:79], v[138:139]
	v_lshlrev_b32_e32 v136, 16, v157
	v_and_b32_e32 v137, 0xffff0000, v157
	v_pk_add_f32 v[84:85], v[84:85], v[136:137]
	v_lshlrev_b32_e32 v138, 16, v161
	v_and_b32_e32 v139, 0xffff0000, v161
	v_pk_add_f32 v[72:73], v[72:73], v[138:139]
	v_lshlrev_b32_e32 v136, 16, v158
	v_and_b32_e32 v137, 0xffff0000, v158
	v_pk_add_f32 v[88:89], v[88:89], v[136:137]
	v_lshlrev_b32_e32 v138, 16, v162
	v_and_b32_e32 v139, 0xffff0000, v162
	v_pk_add_f32 v[76:77], v[76:77], v[138:139]
	v_lshlrev_b32_e32 v136, 16, v159
	v_and_b32_e32 v137, 0xffff0000, v159
	v_pk_add_f32 v[86:87], v[86:87], v[136:137]
	v_lshlrev_b32_e32 v138, 16, v163
	v_and_b32_e32 v139, 0xffff0000, v163
	v_pk_add_f32 v[74:75], v[74:75], v[138:139]
	v_lshlrev_b32_e32 v136, 16, v164
	v_and_b32_e32 v137, 0xffff0000, v164
	v_pk_add_f32 v[94:95], v[94:95], v[136:137]
	v_lshlrev_b32_e32 v138, 16, v168
	v_and_b32_e32 v139, 0xffff0000, v168
	v_pk_add_f32 v[78:79], v[78:79], v[138:139]
	v_lshlrev_b32_e32 v136, 16, v165
	v_and_b32_e32 v137, 0xffff0000, v165
	v_pk_add_f32 v[84:85], v[84:85], v[136:137]
	v_lshlrev_b32_e32 v138, 16, v169
	v_and_b32_e32 v139, 0xffff0000, v169
	v_pk_add_f32 v[72:73], v[72:73], v[138:139]
	v_lshlrev_b32_e32 v136, 16, v166
	v_and_b32_e32 v137, 0xffff0000, v166
	v_pk_add_f32 v[88:89], v[88:89], v[136:137]
	v_lshlrev_b32_e32 v138, 16, v170
	v_and_b32_e32 v139, 0xffff0000, v170
	v_pk_add_f32 v[76:77], v[76:77], v[138:139]
	v_lshlrev_b32_e32 v136, 16, v167
	v_and_b32_e32 v137, 0xffff0000, v167
	v_pk_add_f32 v[86:87], v[86:87], v[136:137]
	v_lshlrev_b32_e32 v138, 16, v171
	v_and_b32_e32 v139, 0xffff0000, v171
	v_pk_add_f32 v[74:75], v[74:75], v[138:139]
	v_cvt_pk_bf16_f32 v68, v94, v95
	v_cvt_pk_bf16_f32 v69, v84, v85
	v_cvt_pk_bf16_f32 v70, v88, v89
	v_cvt_pk_bf16_f32 v71, v86, v87
	global_store_dwordx4 v[80:81], v[68:71], off
	v_lshlrev_b32_e32 v122, 16, v68
	v_and_b32_e32 v123, 0xffff0000, v68
	v_lshlrev_b32_e32 v120, 16, v69
	v_and_b32_e32 v121, 0xffff0000, v69
	v_lshlrev_b32_e32 v118, 16, v70
	v_and_b32_e32 v119, 0xffff0000, v70
	v_lshlrev_b32_e32 v116, 16, v71
	v_and_b32_e32 v117, 0xffff0000, v71
	v_cvt_pk_bf16_f32 v68, v78, v79
	v_cvt_pk_bf16_f32 v69, v72, v73
	v_cvt_pk_bf16_f32 v70, v76, v77
	v_cvt_pk_bf16_f32 v71, v74, v75
	v_lshlrev_b32_e32 v114, 16, v68
	v_and_b32_e32 v115, 0xffff0000, v68
	v_lshlrev_b32_e32 v106, 16, v69
	v_and_b32_e32 v107, 0xffff0000, v69
	v_lshlrev_b32_e32 v104, 16, v70
	v_and_b32_e32 v105, 0xffff0000, v70
	v_lshlrev_b32_e32 v100, 16, v71
	v_and_b32_e32 v101, 0xffff0000, v71
	global_store_dwordx4 v[80:81], v[68:71], off offset:1024
